# sample units rotated: a block whose prompt unit is type t runs the sample unit of type (t+1)%3
# baseline (speedup 1.0000x reference)
.LBB0_317:
	s_add_i32 s4, s34, 0xfffffd00
	s_cmpk_gt_i32 s34, 0x2ff
	s_cselect_b64 s[2:3], -1, 0
	s_and_b64 s[0:1], s[2:3], exec
	s_cselect_b32 s0, s4, s34
	s_mul_hi_i32 s33, s0, 0x55555556
	s_lshr_b32 s1, s33, 31
	s_add_i32 s33, s33, s1
	s_mul_i32 s1, s33, 3
	s_sub_i32 s24, s0, s1
	s_and_b64 s[0:1], s[2:3], exec
	s_cselect_b32 s0, 1, 0
	s_add_i32 s24, s24, s0
	s_cmp_eq_u32 s24, 3
	s_cselect_b32 s24, 0, s24
	s_mov_b64 s[4:5], -1
	s_mov_b64 s[6:7], 0
	s_cmp_lt_i32 s24, 1
	s_mov_b64 s[0:1], 0
	s_cbranch_scc1 .LBB0_341
	s_cmp_eq_u32 s24, 1
	s_mov_b64 s[0:1], -1
	s_cbranch_scc0 .LBB0_352
	s_setprio 1
	s_ashr_i32 s25, s33, 5
	s_and_b64 s[0:1], s[2:3], exec
	s_cselect_b32 s0, 8, 0
	s_add_i32 s25, s25, s0
	s_cmp_lt_i32 s25, 8
	v_mov_b32_e32 v30, v148
	s_cselect_b64 s[8:9], -1, 0
	s_cmp_gt_i32 s25, 7
	s_mov_b64 s[0:1], -1
	s_cbranch_scc0 .LBB0_321
	s_lshl_b32 s0, s25, 6
	s_add_i32 s4, s0, 0x7e80
	s_mov_b64 s[0:1], 0

.LBB0_1020:
	s_add_i32 s4, s34, 0xfffffd00
	s_cmpk_gt_i32 s34, 0x2ff
	s_cselect_b64 s[2:3], -1, 0
	s_and_b64 s[0:1], s[2:3], exec
	s_cselect_b32 s0, s4, s34
	s_mul_hi_i32 s33, s0, 0x55555556
	s_lshr_b32 s1, s33, 31
	s_add_i32 s33, s33, s1
	s_mul_i32 s1, s33, 3
	s_sub_i32 s24, s0, s1
	s_and_b64 s[0:1], s[2:3], exec
	s_cselect_b32 s0, 1, 0
	s_add_i32 s24, s24, s0
	s_cmp_eq_u32 s24, 3
	s_cselect_b32 s24, 0, s24
	s_mov_b64 s[4:5], -1
	s_mov_b64 s[8:9], 0
	s_cmp_lt_i32 s24, 1
	s_mov_b64 s[0:1], 0
	s_cbranch_scc1 .LBB0_1044
	s_cmp_eq_u32 s24, 1
	s_mov_b64 s[0:1], -1
	s_cbranch_scc0 .LBB0_1055
	s_setprio 1
	s_ashr_i32 s25, s33, 5
	s_and_b64 s[0:1], s[2:3], exec
	s_cselect_b32 s0, 8, 0
	s_add_i32 s25, s25, s0
	s_cmp_lt_i32 s25, 8
	v_mov_b32_e32 v30, v148
	s_cselect_b64 s[10:11], -1, 0
	s_cmp_gt_i32 s25, 7
	s_mov_b64 s[0:1], -1
	s_cbranch_scc0 .LBB0_1024
	s_lshl_b32 s0, s25, 6
	s_add_i32 s4, s0, 0x7e80
	s_mov_b64 s[0:1], 0
